# attention steady loop, first step: each QK MFMA issued right behind its gap's tr reads (ahead of the row-sum/pack VALU), no-op lgkmcnt waits dropped
# speedup vs baseline: 1.0050x; 1.0028x over previous
.LBB0_647:
	s_mov_b32 s25, s24
	s_mov_b32 s1, s2
	v_lshl_add_u32 v214, s27, 1, v248
	ds_read_b64_tr_b16 v[66:67], v214 offset:24576
	ds_read_b64_tr_b16 v[68:69], v214 offset:25088
	v_mfma_f32_32x32x16_bf16 v[128:143], v[204:207], v[172:175], 0
	v_add_f32_e32 v65, v96, v97
	v_add_f32_e32 v65, v98, v65
	v_add_f32_e32 v65, v99, v65
	v_add_f32_e32 v65, v100, v65
	v_add_f32_e32 v65, v101, v65
	v_cvt_pk_bf16_f32 v160, v96, v97
	v_cvt_pk_bf16_f32 v161, v98, v99
	ds_read_b64_tr_b16 v[70:71], v214 offset:28672
	ds_read_b64_tr_b16 v[72:73], v214 offset:29184
	v_mfma_f32_32x32x16_bf16 v[112:127], v[200:203], v[172:175], 0
	v_add_f32_e32 v65, v102, v65
	v_add_f32_e32 v65, v103, v65
	v_add_f32_e32 v65, v104, v65
	v_add_f32_e32 v65, v105, v65
	v_cvt_pk_bf16_f32 v162, v100, v101
	v_cvt_pk_bf16_f32 v163, v102, v103
	ds_read_b64_tr_b16 v[74:75], v214 offset:25600
	ds_read_b64_tr_b16 v[76:77], v214 offset:26112
	v_mfma_f32_32x32x16_bf16 v[128:143], v[196:199], v[168:171], v[128:143]
	v_add_f32_e32 v65, v106, v65
	v_add_f32_e32 v65, v107, v65
	v_add_f32_e32 v65, v108, v65
	v_add_f32_e32 v65, v109, v65
	v_cvt_pk_bf16_f32 v152, v104, v105
	v_cvt_pk_bf16_f32 v153, v106, v107
	ds_read_b64_tr_b16 v[96:97], v214 offset:29696
	ds_read_b64_tr_b16 v[98:99], v214 offset:30208
	v_mfma_f32_32x32x16_bf16 v[112:127], v[192:195], v[168:171], v[112:127]
	v_add_f32_e32 v65, v110, v65
	v_add_f32_e32 v65, v111, v65
	v_add_f32_e32 v65, v80, v65
	v_add_f32_e32 v65, v81, v65
	v_cvt_pk_bf16_f32 v154, v108, v109
	v_cvt_pk_bf16_f32 v155, v110, v111
	ds_read_b64_tr_b16 v[100:101], v214 offset:26624
	ds_read_b64_tr_b16 v[102:103], v214 offset:27136
	v_mfma_f32_32x32x16_bf16 v[128:143], v[188:191], v[164:167], v[128:143]
	v_add_f32_e32 v65, v82, v65
	v_add_f32_e32 v65, v83, v65
	v_add_f32_e32 v65, v84, v65
	v_add_f32_e32 v65, v85, v65
	v_cvt_pk_bf16_f32 v148, v80, v81
	v_cvt_pk_bf16_f32 v149, v82, v83
	ds_read_b64_tr_b16 v[104:105], v214 offset:30720
	ds_read_b64_tr_b16 v[106:107], v214 offset:31232
	v_mfma_f32_32x32x16_bf16 v[112:127], v[184:187], v[164:167], v[112:127]
	v_add_f32_e32 v65, v86, v65
	v_add_f32_e32 v65, v87, v65
	v_add_f32_e32 v65, v88, v65
	v_add_f32_e32 v65, v89, v65
	v_cvt_pk_bf16_f32 v150, v84, v85
	v_cvt_pk_bf16_f32 v151, v86, v87
	ds_read_b64_tr_b16 v[108:109], v214 offset:27648
	ds_read_b64_tr_b16 v[110:111], v214 offset:28160
	v_mfma_f32_32x32x16_bf16 v[128:143], v[180:183], v[156:159], v[128:143]
	v_add_f32_e32 v65, v90, v65
	v_add_f32_e32 v65, v91, v65
	v_add_f32_e32 v65, v92, v65
	v_add_f32_e32 v65, v93, v65
	v_cvt_pk_bf16_f32 v144, v88, v89
	v_cvt_pk_bf16_f32 v145, v90, v91
	ds_read_b64_tr_b16 v[86:87], v214 offset:31744
	ds_read_b64_tr_b16 v[88:89], v214 offset:32256
	v_mfma_f32_32x32x16_bf16 v[112:127], v[176:179], v[156:159], v[112:127]
	v_add_f32_e32 v65, v94, v65
	v_add_f32_e32 v65, v95, v65
	v_add_f32_e32 v65, 0, v65
	v_cvt_pk_bf16_f32 v146, v92, v93
	v_cvt_pk_bf16_f32 v147, v94, v95
	s_add_i32 s2, s2, s69
	v_lshl_add_u64 v[78:79], v[212:213], 0, s[16:17]
	s_mov_b32 s24, m0
	s_mov_b32 m0, s2
	s_nop 0
	global_load_lds_dwordx4 v[78:79], off
	s_mov_b32 m0, s24
	s_lshl_b32 s2, s25, 1
	v_lshl_add_u64 v[78:79], v[210:211], 0, s[16:17]
	s_add_i32 s24, s2, s72
	s_mov_b32 s27, m0
	s_mov_b32 m0, s24
	s_nop 0
	global_load_lds_dwordx4 v[78:79], off
	s_mov_b32 m0, s27
	v_lshl_add_u64 v[78:79], v[208:209], 0, s[16:17]
	s_add_i32 s2, s2, s73
	s_mov_b32 s24, m0
	s_mov_b32 m0, s2
	s_nop 0
	global_load_lds_dwordx4 v[78:79], off
	s_mov_b32 m0, s24
	s_waitcnt lgkmcnt(14)
	v_mfma_f32_32x32x16_bf16 v[16:31], v[160:163], v[66:69], v[16:31]
	ds_read_b64_tr_b16 v[90:91], v214 offset:32768
	ds_read_b64_tr_b16 v[92:93], v214 offset:33280
	v_exp_f32_e32 v128, v128
	v_exp_f32_e32 v129, v129
	s_waitcnt lgkmcnt(14)
	v_mfma_f32_32x32x16_bf16 v[48:63], v[160:163], v[70:73], v[48:63]
	ds_read_b64_tr_b16 v[188:189], v214 offset:36864
	ds_read_b64_tr_b16 v[190:191], v214 offset:37376
	v_exp_f32_e32 v130, v130
	v_exp_f32_e32 v131, v131
	v_add_u32_e32 v66, s25, v246
	ds_read_b128 v[82:85], v66
	ds_read_b128 v[78:81], v66 offset:512
	s_waitcnt lgkmcnt(14)
	v_mfma_f32_32x32x16_bf16 v[16:31], v[152:155], v[74:77], v[16:31]
	ds_read_b64_tr_b16 v[192:193], v214 offset:33792
	ds_read_b64_tr_b16 v[194:195], v214 offset:34304
	v_exp_f32_e32 v132, v132
	v_exp_f32_e32 v133, v133
	ds_read_b128 v[184:187], v66 offset:2048
	ds_read_b128 v[176:179], v66 offset:2560
	v_mfma_f32_32x32x16_bf16 v[48:63], v[152:155], v[96:99], v[48:63]
	ds_read_b64_tr_b16 v[196:197], v214 offset:37888
	ds_read_b64_tr_b16 v[198:199], v214 offset:38400
	v_exp_f32_e32 v134, v134
	v_exp_f32_e32 v135, v135
	ds_read_b128 v[180:183], v66 offset:4096
	ds_read_b128 v[70:73], v66 offset:4608
	s_waitcnt lgkmcnt(14)
	v_mfma_f32_32x32x16_bf16 v[16:31], v[148:151], v[100:103], v[16:31]
	ds_read_b64_tr_b16 v[94:95], v214 offset:34816
	ds_read_b64_tr_b16 v[96:97], v214 offset:35328
	v_exp_f32_e32 v136, v136
	v_exp_f32_e32 v137, v137
	ds_read_b128 v[74:77], v66 offset:6144
	ds_read_b128 v[66:69], v66 offset:6656
	v_mfma_f32_32x32x16_bf16 v[48:63], v[148:151], v[104:107], v[48:63]
	ds_read_b64_tr_b16 v[98:99], v214 offset:38912
	ds_read_b64_tr_b16 v[100:101], v214 offset:39424
	v_exp_f32_e32 v138, v138
	v_exp_f32_e32 v139, v139
	v_mfma_f32_32x32x16_bf16 v[16:31], v[144:147], v[108:111], v[16:31]
	ds_read_b64_tr_b16 v[102:103], v214 offset:35840
	ds_read_b64_tr_b16 v[104:105], v214 offset:36352
	v_exp_f32_e32 v140, v140
	v_exp_f32_e32 v141, v141
	v_mfma_f32_32x32x16_bf16 v[48:63], v[144:147], v[86:89], v[48:63]
	ds_read_b64_tr_b16 v[106:107], v214 offset:39936
	ds_read_b64_tr_b16 v[108:109], v214 offset:40448
	v_exp_f32_e32 v142, v142
	v_exp_f32_e32 v143, v143
	s_waitcnt lgkmcnt(14)
	v_mfma_f32_32x32x16_bf16 v[0:15], v[160:163], v[90:93], v[0:15]
	v_exp_f32_e32 v112, v112
	v_exp_f32_e32 v113, v113
	v_mfma_f32_32x32x16_bf16 v[32:47], v[160:163], v[188:191], v[32:47]
	v_exp_f32_e32 v114, v114
	v_exp_f32_e32 v115, v115
	v_mfma_f32_32x32x16_bf16 v[0:15], v[152:155], v[192:195], v[0:15]
	v_exp_f32_e32 v116, v116
	v_exp_f32_e32 v117, v117
	s_waitcnt lgkmcnt(12)
	v_mfma_f32_32x32x16_bf16 v[32:47], v[152:155], v[196:199], v[32:47]
	v_exp_f32_e32 v118, v118
	v_exp_f32_e32 v119, v119
	s_waitcnt lgkmcnt(8)
	v_mfma_f32_32x32x16_bf16 v[0:15], v[148:151], v[94:97], v[0:15]
	v_exp_f32_e32 v120, v120
	v_exp_f32_e32 v121, v121
	s_waitcnt lgkmcnt(4)
	v_mfma_f32_32x32x16_bf16 v[32:47], v[148:151], v[98:101], v[32:47]
	v_exp_f32_e32 v122, v122
	v_exp_f32_e32 v123, v123
	s_waitcnt lgkmcnt(2)
	v_mfma_f32_32x32x16_bf16 v[0:15], v[144:147], v[102:105], v[0:15]
	v_exp_f32_e32 v124, v124
	v_exp_f32_e32 v125, v125
	s_waitcnt lgkmcnt(0)
	v_mfma_f32_32x32x16_bf16 v[32:47], v[144:147], v[106:109], v[32:47]
	v_exp_f32_e32 v126, v126
	v_exp_f32_e32 v127, v127
	s_waitcnt vmcnt(3) lgkmcnt(0)
	s_barrier
	s_add_i32 s2, s25, 0x2000
	s_cmpk_lg_i32 s25, 0x4000
	s_cselect_b32 s2, s2, 0
	v_lshl_add_u32 v214, s1, 1, v248
	ds_read_b64_tr_b16 v[188:189], v214 offset:24576
	ds_read_b64_tr_b16 v[190:191], v214 offset:25088
	v_mfma_f32_32x32x16_bf16 v[96:111], v[82:85], v[172:175], 0
	v_add_f32_e32 v86, v128, v129
	v_add_f32_e32 v86, v130, v86
	v_add_f32_e32 v86, v131, v86
	v_add_f32_e32 v86, v132, v86
	v_add_f32_e32 v86, v133, v86
	v_cvt_pk_bf16_f32 v160, v128, v129
	v_cvt_pk_bf16_f32 v161, v130, v131
	ds_read_b64_tr_b16 v[128:129], v214 offset:28672
	ds_read_b64_tr_b16 v[130:131], v214 offset:29184
	v_add_f32_e32 v82, v134, v86
	v_add_f32_e32 v82, v135, v82
	v_add_f32_e32 v82, v136, v82
	v_add_f32_e32 v144, v137, v82
	v_mfma_f32_32x32x16_bf16 v[80:95], v[78:81], v[172:175], 0
	v_cvt_pk_bf16_f32 v162, v132, v133
	v_cvt_pk_bf16_f32 v163, v134, v135
	ds_read_b64_tr_b16 v[132:133], v214 offset:25600
	ds_read_b64_tr_b16 v[134:135], v214 offset:26112
	v_mfma_f32_32x32x16_bf16 v[96:111], v[184:187], v[168:171], v[96:111]
	v_add_f32_e32 v78, v138, v144
	v_add_f32_e32 v78, v139, v78
	v_add_f32_e32 v78, v140, v78
	v_add_f32_e32 v78, v141, v78
	v_cvt_pk_bf16_f32 v152, v136, v137
	v_cvt_pk_bf16_f32 v153, v138, v139
	ds_read_b64_tr_b16 v[136:137], v214 offset:29696
	ds_read_b64_tr_b16 v[138:139], v214 offset:30208
	v_mfma_f32_32x32x16_bf16 v[80:95], v[176:179], v[168:171], v[80:95]
	v_add_f32_e32 v78, v142, v78
	v_add_f32_e32 v78, v143, v78
	v_add_f32_e32 v78, v112, v78
	v_add_f32_e32 v78, v113, v78
	v_cvt_pk_bf16_f32 v154, v140, v141
	v_cvt_pk_bf16_f32 v155, v142, v143
	ds_read_b64_tr_b16 v[140:141], v214 offset:26624
	ds_read_b64_tr_b16 v[142:143], v214 offset:27136
	v_mfma_f32_32x32x16_bf16 v[96:111], v[180:183], v[164:167], v[96:111]
	v_add_f32_e32 v78, v114, v78
	v_add_f32_e32 v78, v115, v78
	v_add_f32_e32 v78, v116, v78
	v_add_f32_e32 v78, v117, v78
	v_cvt_pk_bf16_f32 v148, v112, v113
	v_cvt_pk_bf16_f32 v149, v114, v115
	ds_read_b64_tr_b16 v[112:113], v214 offset:30720
	ds_read_b64_tr_b16 v[114:115], v214 offset:31232
	v_mfma_f32_32x32x16_bf16 v[80:95], v[70:73], v[164:167], v[80:95]
	v_add_f32_e32 v78, v118, v78
	v_add_f32_e32 v78, v119, v78
	v_add_f32_e32 v78, v120, v78
	v_add_f32_e32 v78, v121, v78
	v_cvt_pk_bf16_f32 v150, v116, v117
	v_cvt_pk_bf16_f32 v151, v118, v119
	ds_read_b64_tr_b16 v[70:71], v214 offset:27648
	ds_read_b64_tr_b16 v[72:73], v214 offset:28160
	v_mfma_f32_32x32x16_bf16 v[96:111], v[74:77], v[156:159], v[96:111]
	v_add_f32_e32 v78, v122, v78
	v_add_f32_e32 v78, v123, v78
	v_add_f32_e32 v78, v124, v78
	v_add_f32_e32 v78, v125, v78
	v_cvt_pk_bf16_f32 v144, v120, v121
	v_cvt_pk_bf16_f32 v145, v122, v123
	ds_read_b64_tr_b16 v[74:75], v214 offset:31744
	ds_read_b64_tr_b16 v[76:77], v214 offset:32256
	v_mfma_f32_32x32x16_bf16 v[80:95], v[66:69], v[156:159], v[80:95]
	v_add_f32_e32 v78, v126, v78
	v_add_f32_e32 v78, v127, v78
	v_add_f32_e32 v78, 0, v78
	v_cvt_pk_bf16_f32 v146, v124, v125
	v_cvt_pk_bf16_f32 v147, v126, v127
	s_add_i32 s1, s25, s69
	s_mov_b32 s24, m0
	s_mov_b32 m0, s1
	s_nop 0
	global_load_lds_dwordx4 v[212:213], off
	s_mov_b32 m0, s24
	s_lshl_b32 s1, s2, 1
	s_add_i32 s24, s1, s72
	s_mov_b32 s27, m0
	s_mov_b32 m0, s24
	s_nop 0
	global_load_lds_dwordx4 v[210:211], off
	s_mov_b32 m0, s27
	s_add_i32 s1, s1, s73
	s_mov_b32 s24, m0
	s_mov_b32 m0, s1
	s_nop 0
	global_load_lds_dwordx4 v[208:209], off
	s_mov_b32 m0, s24
	s_add_i32 s8, s8, 2
	s_waitcnt lgkmcnt(14)
	v_mfma_f32_32x32x16_bf16 v[16:31], v[160:163], v[188:191], v[16:31]
	ds_read_b64_tr_b16 v[66:67], v214 offset:32768
	ds_read_b64_tr_b16 v[68:69], v214 offset:33280
	v_exp_f32_e32 v96, v96
	v_exp_f32_e32 v97, v97
	s_waitcnt lgkmcnt(14)
	v_mfma_f32_32x32x16_bf16 v[48:63], v[160:163], v[128:131], v[48:63]
	ds_read_b64_tr_b16 v[116:117], v214 offset:36864
	ds_read_b64_tr_b16 v[118:119], v214 offset:37376
	v_exp_f32_e32 v98, v98
	v_exp_f32_e32 v99, v99
	v_add_u32_e32 v79, s2, v246
	ds_read_b128 v[204:207], v79
	ds_read_b128 v[200:203], v79 offset:512
	s_waitcnt lgkmcnt(14)
	v_mfma_f32_32x32x16_bf16 v[16:31], v[152:155], v[132:135], v[16:31]
	ds_read_b64_tr_b16 v[120:121], v214 offset:33792
	ds_read_b64_tr_b16 v[122:123], v214 offset:34304
	v_exp_f32_e32 v100, v100
	v_exp_f32_e32 v101, v101
	ds_read_b128 v[196:199], v79 offset:2048
	ds_read_b128 v[192:195], v79 offset:2560
	v_mfma_f32_32x32x16_bf16 v[48:63], v[152:155], v[136:139], v[48:63]
	ds_read_b64_tr_b16 v[124:125], v214 offset:37888
	ds_read_b64_tr_b16 v[126:127], v214 offset:38400
	v_exp_f32_e32 v102, v102
	v_exp_f32_e32 v103, v103
	ds_read_b128 v[188:191], v79 offset:4096
	ds_read_b128 v[184:187], v79 offset:4608
	s_waitcnt lgkmcnt(14)
	v_mfma_f32_32x32x16_bf16 v[16:31], v[148:151], v[140:143], v[16:31]
	ds_read_b64_tr_b16 v[128:129], v214 offset:34816
	ds_read_b64_tr_b16 v[130:131], v214 offset:35328
	v_exp_f32_e32 v104, v104
	v_exp_f32_e32 v105, v105
	ds_read_b128 v[180:183], v79 offset:6144
	ds_read_b128 v[176:179], v79 offset:6656
	v_mfma_f32_32x32x16_bf16 v[48:63], v[148:151], v[112:115], v[48:63]
	ds_read_b64_tr_b16 v[132:133], v214 offset:38912
	ds_read_b64_tr_b16 v[134:135], v214 offset:39424
	v_exp_f32_e32 v106, v106
	v_exp_f32_e32 v107, v107
	v_mfma_f32_32x32x16_bf16 v[16:31], v[144:147], v[70:73], v[16:31]
	ds_read_b64_tr_b16 v[112:113], v214 offset:35840
	ds_read_b64_tr_b16 v[114:115], v214 offset:36352
	v_exp_f32_e32 v108, v108
	v_exp_f32_e32 v109, v109
	v_mfma_f32_32x32x16_bf16 v[48:63], v[144:147], v[74:77], v[48:63]
	ds_read_b64_tr_b16 v[70:71], v214 offset:39936
	ds_read_b64_tr_b16 v[72:73], v214 offset:40448
	v_exp_f32_e32 v110, v110
	v_exp_f32_e32 v111, v111
	s_waitcnt lgkmcnt(14)
	v_mfma_f32_32x32x16_bf16 v[0:15], v[160:163], v[66:69], v[0:15]
	v_exp_f32_e32 v80, v80
	v_exp_f32_e32 v81, v81
	v_mfma_f32_32x32x16_bf16 v[32:47], v[160:163], v[116:119], v[32:47]
	v_exp_f32_e32 v82, v82
	v_exp_f32_e32 v83, v83
	v_mfma_f32_32x32x16_bf16 v[0:15], v[152:155], v[120:123], v[0:15]
	v_exp_f32_e32 v84, v84
	v_exp_f32_e32 v85, v85
	s_waitcnt lgkmcnt(12)
	v_mfma_f32_32x32x16_bf16 v[32:47], v[152:155], v[124:127], v[32:47]
	v_exp_f32_e32 v86, v86
	v_exp_f32_e32 v87, v87
	s_waitcnt lgkmcnt(8)
	v_mfma_f32_32x32x16_bf16 v[0:15], v[148:151], v[128:131], v[0:15]
	v_exp_f32_e32 v88, v88
	v_exp_f32_e32 v89, v89
	s_waitcnt lgkmcnt(4)
	v_mfma_f32_32x32x16_bf16 v[32:47], v[148:151], v[132:135], v[32:47]
	v_exp_f32_e32 v90, v90
	v_exp_f32_e32 v91, v91
	s_waitcnt lgkmcnt(2)
	v_mfma_f32_32x32x16_bf16 v[0:15], v[144:147], v[112:115], v[0:15]
	v_exp_f32_e32 v92, v92
	v_exp_f32_e32 v93, v93
	s_waitcnt lgkmcnt(0)
	v_mfma_f32_32x32x16_bf16 v[32:47], v[144:147], v[70:73], v[32:47]
	v_exp_f32_e32 v94, v94
	v_exp_f32_e32 v95, v95
	s_waitcnt vmcnt(3) lgkmcnt(0)
	s_barrier
	s_add_i32 s1, s2, 0x2000
	v_add_f32_e32 v64, v64, v65
	s_cmpk_lg_i32 s2, 0x4000
	v_lshl_add_u64 v[208:209], v[208:209], 0, s[12:13]
	v_lshl_add_u64 v[210:211], v[210:211], 0, s[12:13]
	v_lshl_add_u64 v[212:213], v[212:213], 0, s[12:13]
	s_mov_b32 s27, s25
	s_cselect_b32 s24, s1, 0
	s_cmp_ge_i32 s8, s0
	v_add_f32_e32 v64, v64, v78
	s_cbranch_scc0 .LBB0_647
	s_add_i32 s0, s8, 1
	s_cmp_ge_i32 s0, s26
	s_mov_b64 s[0:1], -1
	s_cbranch_scc0 .LBB0_650
